# attention KV loop: s_setprio 1 around each 8-MFMA group (QK^T and PV), 0 elsewhere, replacing the static priority of waves 4-7
# baseline (speedup 1.0000x reference)
.LBB0_877:
	s_and_b64 vcc, exec, s[2:3]
	s_cbranch_vccz .LBB0_1227
	v_readlane_b32 s0, v254, 1
	s_cmpk_gt_i32 s0, 0x1ff
	s_waitcnt vmcnt(0)
	v_ashrrev_i32_e32 v130, 3, v200
	s_movk_i32 s0, 0xffe0
	v_and_b32_e32 v167, 31, v200
	v_bfe_u32 v0, v200, 5, 1
	s_waitcnt vmcnt(0)
	v_and_b32_e32 v2, 7, v200
	v_bfi_b32 v137, s0, v130, v200
	s_movk_i32 s0, 0x90
	v_and_b32_e32 v135, 0xc0, v200
	v_lshlrev_b32_e32 v134, 3, v0
	v_ashrrev_i32_e32 v131, 31, v130
	v_lshlrev_b32_e32 v136, 3, v2
	v_lshlrev_b32_e32 v132, 4, v2
	v_mul_lo_u32 v166, v130, s0
	v_lshl_add_u32 v139, v0, 4, s36
	v_mul_u32_u24_e32 v155, 0x90, v167
	v_lshlrev_b32_e32 v138, 2, v0
	v_readlane_b32 s1, v254, 2
	s_cbranch_scc1 .LBB0_893
	s_add_u32 s0, s12, 0x13700000
	s_addc_u32 s1, s13, 0
	s_mul_i32 s7, s37, 0x480000
	s_mul_hi_i32 s6, s37, 0x480000
	s_add_u32 s4, s0, s7
	s_addc_u32 s8, s1, s6
	s_add_i32 s2, s37, 2
	s_add_i32 s3, s7, 0x900000
	s_mul_hi_i32 s2, s2, 0x480000
	s_add_u32 s0, s0, s3
	s_addc_u32 s1, s1, s2
	v_mov_b64_e32 v[2:3], s[0:1]
	s_movk_i32 s14, 0x1200
	v_mad_i64_i32 v[2:3], s[0:1], v130, s14, v[2:3]
	s_cmpk_eq_i32 s5, 0x100
	v_readlane_b32 s10, v254, 1
	v_mov_b32_e32 v133, v1
	s_movk_i32 s0, 0x88
	s_cselect_b64 s[2:3], -1, 0
	v_readlane_b32 s11, v254, 2
	s_mov_b32 s16, s10
	s_lshl_b32 s10, s10, 1
	v_lshl_add_u64 v[142:143], v[2:3], 0, v[132:133]
	v_mul_lo_u32 v2, v130, s0
	s_and_b32 s10, s10, 14
	s_ashr_i32 s11, s16, 3
	v_add_u32_e32 v169, s36, v2
	v_xor_b32_e32 v2, 32, v224
	v_add_u32_e32 v3, 64, v225
	v_cmp_lt_i32_e32 vcc, v2, v3
	s_add_u32 s0, s12, s7
	s_addc_u32 s1, s13, s6
	v_cndmask_b32_e32 v2, v224, v2, vcc
	v_lshlrev_b64 v[140:141], 8, v[130:131]
	v_add_u32_e32 v0, s36, v166
	v_add_u32_e32 v4, s36, v134
	v_mul_u32_u24_e32 v5, 0x88, v167
	v_lshlrev_b32_e32 v170, 2, v2
	v_mov_b64_e32 v[2:3], s[0:1]
	v_add_u32_e32 v168, 0x1000, v137
	v_mad_i64_i32 v[144:145], s[6:7], v130, s14, v[2:3]
	v_lshl_add_u64 v[146:147], s[0:1], 0, v[140:141]
	v_lshlrev_b32_e32 v148, 1, v134
	v_lshlrev_b32_e32 v150, 1, v136
	v_lshlrev_b32_e32 v152, 1, v138
	v_add_u32_e32 v171, v0, v132
	v_add_u32_e32 v172, v139, v155
	v_add_u32_e32 v173, v4, v5
	v_readfirstlane_b32 s0, v191
	s_cmpk_lt_u32 s0, 0x100
	s_cbranch_scc1 .Lattn_prio_skip
.Lattn_prio_skip:
	s_branch .LBB0_881

.LBB0_885:
	ds_read_b128 v[34:37], v172
	ds_read_b128 v[38:41], v172 offset:32
	ds_read_b128 v[42:45], v172 offset:64
	ds_read_b128 v[46:49], v172 offset:96
	ds_read_b128 v[98:101], v172 offset:4608
	ds_read_b128 v[102:105], v172 offset:4640
	ds_read_b128 v[106:109], v172 offset:4672
	ds_read_b128 v[110:113], v172 offset:4704
	s_setprio 1
	s_waitcnt vmcnt(5) lgkmcnt(7)
	v_mfma_f32_32x32x16_bf16 v[50:65], v[34:37], v[66:69], v[206:221]
	v_add_u32_e32 v0, 0x2000, v173
	ds_read2_b64 v[126:129], v0 offset0:128 offset1:130
	ds_read2_b64 v[114:117], v0 offset0:132 offset1:134
	s_waitcnt vmcnt(4) lgkmcnt(8)
	v_mfma_f32_32x32x16_bf16 v[50:65], v[38:41], v[70:73], v[50:65]
	s_waitcnt vmcnt(1) lgkmcnt(7)
	v_mfma_f32_32x32x16_bf16 v[50:65], v[42:45], v[78:81], v[50:65]
	s_waitcnt vmcnt(0) lgkmcnt(6)
	v_mfma_f32_32x32x16_bf16 v[50:65], v[46:49], v[82:85], v[50:65]
	s_waitcnt lgkmcnt(5)
	v_mfma_f32_32x32x16_bf16 v[34:49], v[98:101], v[66:69], v[206:221]
	v_add_u32_e32 v98, 0x3000, v173
	s_waitcnt lgkmcnt(4)
	v_mfma_f32_32x32x16_bf16 v[34:49], v[102:105], v[70:73], v[34:49]
	s_waitcnt lgkmcnt(3)
	v_mfma_f32_32x32x16_bf16 v[34:49], v[106:109], v[78:81], v[34:49]
	s_waitcnt lgkmcnt(2)
	v_mfma_f32_32x32x16_bf16 v[34:49], v[110:113], v[82:85], v[34:49]
	ds_read2_b64 v[122:125], v98 offset0:160 offset1:162
	ds_read2_b64 v[118:121], v98 offset0:164 offset1:166
	ds_read2_b64 v[110:113], v0 offset0:136 offset1:138
	ds_read2_b64 v[106:109], v98 offset0:168 offset1:170
	ds_read2_b64 v[102:105], v0 offset0:140 offset1:142
	ds_read2_b64 v[98:101], v98 offset0:172 offset1:174
	s_setprio 0
	v_max_f32_e32 v0, v51, v51
	v_max_f32_e32 v174, v50, v50
	v_max_f32_e32 v0, v174, v0
	v_max3_f32 v0, v0, v52, v53
	v_max3_f32 v0, v0, v54, v55
	v_max3_f32 v0, v0, v56, v57
	v_max3_f32 v0, v0, v58, v59
	v_max3_f32 v0, v0, v60, v61
	v_max3_f32 v0, v0, v62, v63
	v_max3_f32 v0, v0, v64, v65
	v_max3_f32 v0, v0, v34, v35
	v_max3_f32 v0, v0, v36, v37
	v_max3_f32 v0, v0, v38, v39
	v_max3_f32 v0, v0, v40, v41
	v_max3_f32 v0, v0, v42, v43
	v_max3_f32 v0, v0, v44, v45
	v_max3_f32 v0, v0, v46, v47
	v_max3_f32 v0, v0, v48, v49
	ds_bpermute_b32 v174, v170, v0
	s_waitcnt lgkmcnt(0)
	v_max_f32_e32 v174, v174, v174
	v_max_f32_e32 v0, v0, v174
	v_cmp_lt_f32_e32 vcc, s98, v0
	s_cbranch_vccz .LBB0_887
	v_max_f32_e32 v174, s99, v0
	v_sub_f32_e32 v0, 0, v174
	v_min_f32_e32 v0, 0, v0
	v_exp_f32_e32 v0, v0
	v_sub_f32_e32 v206, v206, v174
	v_add_f32_e32 v151, v151, v174
	v_mov_b32_e32 v207, v206
	v_mov_b32_e32 v208, v206
	v_mov_b32_e32 v209, v206
	v_mov_b32_e32 v210, v206
	v_mov_b32_e32 v211, v206
	v_mov_b32_e32 v212, v206
	v_mov_b32_e32 v213, v206
	v_mov_b32_e32 v214, v206
	v_mov_b32_e32 v215, v206
	v_mov_b32_e32 v216, v206
	v_mov_b32_e32 v217, v206
	v_mov_b32_e32 v218, v206
	v_mov_b32_e32 v219, v206
	v_mov_b32_e32 v220, v206
	v_mov_b32_e32 v221, v206
	v_mul_f32_e32 v153, v153, v0
	v_mul_f32_e32 v32, v32, v0
	v_mul_f32_e32 v33, v33, v0
	v_mul_f32_e32 v30, v30, v0
	v_mul_f32_e32 v31, v31, v0
	v_mul_f32_e32 v28, v28, v0
	v_mul_f32_e32 v29, v29, v0
	v_mul_f32_e32 v26, v26, v0
	v_mul_f32_e32 v27, v27, v0
	v_mul_f32_e32 v24, v24, v0
	v_mul_f32_e32 v25, v25, v0
	v_mul_f32_e32 v22, v22, v0
	v_mul_f32_e32 v23, v23, v0
	v_mul_f32_e32 v20, v20, v0
	v_mul_f32_e32 v21, v21, v0
	v_mul_f32_e32 v18, v18, v0
	v_mul_f32_e32 v19, v19, v0
	v_mul_f32_e32 v16, v16, v0
	v_mul_f32_e32 v17, v17, v0
	v_mul_f32_e32 v14, v14, v0
	v_mul_f32_e32 v15, v15, v0
	v_mul_f32_e32 v12, v12, v0
	v_mul_f32_e32 v13, v13, v0
	v_mul_f32_e32 v10, v10, v0
	v_mul_f32_e32 v11, v11, v0
	v_mul_f32_e32 v8, v8, v0
	v_mul_f32_e32 v9, v9, v0
	v_mul_f32_e32 v6, v6, v0
	v_mul_f32_e32 v7, v7, v0
	v_mul_f32_e32 v4, v4, v0
	v_mul_f32_e32 v5, v5, v0
	v_mul_f32_e32 v2, v2, v0
	v_mul_f32_e32 v3, v3, v0
	v_sub_f32_e32 v50, v50, v174
	v_sub_f32_e32 v51, v51, v174
	v_sub_f32_e32 v52, v52, v174
	v_sub_f32_e32 v53, v53, v174
	v_sub_f32_e32 v54, v54, v174
	v_sub_f32_e32 v55, v55, v174
	v_sub_f32_e32 v56, v56, v174
	v_sub_f32_e32 v57, v57, v174
	v_sub_f32_e32 v58, v58, v174
	v_sub_f32_e32 v59, v59, v174
	v_sub_f32_e32 v60, v60, v174
	v_sub_f32_e32 v61, v61, v174
	v_sub_f32_e32 v62, v62, v174
	v_sub_f32_e32 v63, v63, v174
	v_sub_f32_e32 v64, v64, v174
	v_sub_f32_e32 v65, v65, v174
	v_sub_f32_e32 v34, v34, v174
	v_sub_f32_e32 v35, v35, v174
	v_sub_f32_e32 v36, v36, v174
	v_sub_f32_e32 v37, v37, v174
	v_sub_f32_e32 v38, v38, v174
	v_sub_f32_e32 v39, v39, v174
	v_sub_f32_e32 v40, v40, v174
	v_sub_f32_e32 v41, v41, v174
	v_sub_f32_e32 v42, v42, v174
	v_sub_f32_e32 v43, v43, v174
	v_sub_f32_e32 v44, v44, v174
	v_sub_f32_e32 v45, v45, v174
	v_sub_f32_e32 v46, v46, v174
	v_sub_f32_e32 v47, v47, v174
	v_sub_f32_e32 v48, v48, v174
	v_sub_f32_e32 v49, v49, v174
	s_mov_b32 s98, 0x41000000
	s_mov_b32 s99, 0
.LBB0_887:
	v_exp_f32_e32 v0, v50
	v_exp_f32_e32 v50, v51
	v_exp_f32_e32 v51, v52
	v_exp_f32_e32 v52, v53
	v_exp_f32_e32 v53, v54
	v_exp_f32_e32 v54, v55
	v_exp_f32_e32 v55, v56
	v_exp_f32_e32 v56, v57
	v_exp_f32_e32 v57, v58
	v_exp_f32_e32 v58, v59
	v_exp_f32_e32 v59, v60
	v_exp_f32_e32 v60, v61
	v_exp_f32_e32 v61, v62
	v_exp_f32_e32 v62, v63
	v_exp_f32_e32 v63, v64
	v_exp_f32_e32 v64, v65
	v_exp_f32_e32 v34, v34
	v_exp_f32_e32 v35, v35
	v_exp_f32_e32 v36, v36
	v_exp_f32_e32 v37, v37
	v_exp_f32_e32 v38, v38
	v_exp_f32_e32 v39, v39
	v_exp_f32_e32 v40, v40
	v_exp_f32_e32 v41, v41
	v_exp_f32_e32 v42, v42
	v_exp_f32_e32 v43, v43
	v_exp_f32_e32 v44, v44
	v_exp_f32_e32 v45, v45
	v_exp_f32_e32 v46, v46
	v_exp_f32_e32 v47, v47
	v_exp_f32_e32 v48, v48
	v_exp_f32_e32 v49, v49
	v_cvt_pk_bf16_f32 v174, v0, v50
	v_cvt_pk_bf16_f32 v175, v51, v52
	v_cvt_pk_bf16_f32 v176, v53, v54
	v_cvt_pk_bf16_f32 v177, v55, v56
	v_cvt_pk_bf16_f32 v178, v57, v58
	v_cvt_pk_bf16_f32 v179, v59, v60
	v_cvt_pk_bf16_f32 v180, v61, v62
	v_cvt_pk_bf16_f32 v181, v63, v64
	v_cvt_pk_bf16_f32 v182, v34, v35
	v_cvt_pk_bf16_f32 v183, v36, v37
	v_cvt_pk_bf16_f32 v184, v38, v39
	v_cvt_pk_bf16_f32 v185, v40, v41
	v_cvt_pk_bf16_f32 v186, v42, v43
	v_cvt_pk_bf16_f32 v187, v44, v45
	v_cvt_pk_bf16_f32 v188, v46, v47
	v_cvt_pk_bf16_f32 v189, v48, v49
	s_setprio 1
	v_mfma_f32_32x32x16_bf16 v[2:17], v[126:129], v[174:177], v[2:17]
	v_mfma_f32_32x32x16_bf16 v[18:33], v[122:125], v[174:177], v[18:33]
	v_mfma_f32_32x32x16_bf16 v[2:17], v[114:117], v[178:181], v[2:17]
	v_mfma_f32_32x32x16_bf16 v[18:33], v[118:121], v[178:181], v[18:33]
	v_mfma_f32_32x32x16_bf16 v[2:17], v[110:113], v[182:185], v[2:17]
	v_mfma_f32_32x32x16_bf16 v[18:33], v[106:109], v[182:185], v[18:33]
	v_mfma_f32_32x32x16_bf16 v[2:17], v[102:105], v[186:189], v[2:17]
	v_mfma_f32_32x32x16_bf16 v[18:33], v[98:101], v[186:189], v[18:33]
	s_setprio 0
	s_movk_i32 s0, 0x6a00
	v_add3_u32 v65, v169, v132, s0
	s_cmp_gt_u32 s17, 32
	ds_write_b128 v171, v[86:89] offset:17920
	ds_write2_b64 v65, v[94:95], v[96:97] offset1:1
	s_waitcnt lgkmcnt(0)
	s_barrier
	s_cbranch_scc1 .LBB0_889
	v_add_co_u32_e32 v86, vcc, 0x1370c000, v164
	s_nop 1
	v_addc_co_u32_e32 v87, vcc, 0, v165, vcc
	v_add_co_u32_e32 v94, vcc, 0x14000000, v162
	global_load_dwordx4 v[86:89], v[86:87], off
	s_nop 0
	v_addc_co_u32_e32 v95, vcc, 0, v163, vcc
	global_load_dwordx4 v[94:97], v[94:95], off offset:384
.LBB0_889:
	v_add_f32_e32 v0, 0, v0
	v_add_f32_e32 v0, v50, v0
	v_add_f32_e32 v0, v51, v0
	v_add_f32_e32 v0, v52, v0
	v_add_f32_e32 v0, v53, v0
	v_add_f32_e32 v0, v54, v0
	v_add_f32_e32 v0, v55, v0
	v_add_f32_e32 v0, v56, v0
	v_add_f32_e32 v0, v57, v0
	v_add_f32_e32 v0, v58, v0
	v_add_f32_e32 v0, v59, v0
	v_add_f32_e32 v0, v60, v0
	v_add_f32_e32 v0, v61, v0
	v_add_f32_e32 v0, v62, v0
	v_add_f32_e32 v0, v63, v0
	v_add_f32_e32 v0, v64, v0
	v_add_f32_e32 v0, v34, v0
	v_add_f32_e32 v0, v35, v0
	v_add_f32_e32 v0, v36, v0
	v_add_f32_e32 v0, v37, v0
	v_add_f32_e32 v0, v38, v0
	v_add_f32_e32 v0, v39, v0
	v_add_f32_e32 v0, v40, v0
	v_add_f32_e32 v0, v41, v0
	v_add_f32_e32 v0, v42, v0
	v_add_f32_e32 v0, v43, v0
	v_add_f32_e32 v0, v44, v0
	v_add_f32_e32 v0, v45, v0
	v_add_f32_e32 v0, v46, v0
	v_add_f32_e32 v0, v47, v0
	v_add_f32_e32 v0, v48, v0
	v_add_f32_e32 v0, v49, v0
	ds_read_b128 v[34:37], v172 offset:17920
	ds_read_b128 v[38:41], v172 offset:17952
	ds_read_b128 v[42:45], v172 offset:17984
	ds_read_b128 v[46:49], v172 offset:18016
	ds_read_b128 v[98:101], v172 offset:22528
	ds_read_b128 v[102:105], v172 offset:22560
	ds_read_b128 v[106:109], v172 offset:22592
	ds_read_b128 v[110:113], v172 offset:22624
	v_add_f32_e32 v0, v153, v0
	s_setprio 1
	s_waitcnt lgkmcnt(7)
	v_mfma_f32_32x32x16_bf16 v[50:65], v[34:37], v[66:69], v[206:221]
	s_waitcnt lgkmcnt(6)
	v_mfma_f32_32x32x16_bf16 v[50:65], v[38:41], v[70:73], v[50:65]
	s_waitcnt lgkmcnt(5)
	v_mfma_f32_32x32x16_bf16 v[50:65], v[42:45], v[78:81], v[50:65]
	s_waitcnt lgkmcnt(4)
	v_mfma_f32_32x32x16_bf16 v[50:65], v[46:49], v[82:85], v[50:65]
	s_waitcnt lgkmcnt(3)
	v_mfma_f32_32x32x16_bf16 v[34:49], v[98:101], v[66:69], v[206:221]
	v_add_u32_e32 v98, 0x6800, v173
	v_add_u32_e32 v99, 0x7800, v173
	ds_read2_b64 v[126:129], v98 offset0:64 offset1:66
	ds_read2_b64 v[114:117], v98 offset0:68 offset1:70
	s_waitcnt lgkmcnt(4)
	v_mfma_f32_32x32x16_bf16 v[34:49], v[102:105], v[70:73], v[34:49]
	s_waitcnt lgkmcnt(3)
	v_mfma_f32_32x32x16_bf16 v[34:49], v[106:109], v[78:81], v[34:49]
	s_waitcnt lgkmcnt(2)
	v_mfma_f32_32x32x16_bf16 v[34:49], v[110:113], v[82:85], v[34:49]
	ds_read2_b64 v[122:125], v99 offset0:96 offset1:98
	ds_read2_b64 v[118:121], v99 offset0:100 offset1:102
	ds_read2_b64 v[110:113], v98 offset0:72 offset1:74
	ds_read2_b64 v[106:109], v99 offset0:104 offset1:106
	ds_read2_b64 v[102:105], v98 offset0:76 offset1:78
	ds_read2_b64 v[98:101], v99 offset0:108 offset1:110
	s_setprio 0
	v_max_f32_e32 v153, v51, v51
	v_max_f32_e32 v162, v50, v50
	v_max_f32_e32 v153, v162, v153
	v_max3_f32 v153, v153, v52, v53
	v_max3_f32 v153, v153, v54, v55
	v_max3_f32 v153, v153, v56, v57
	v_max3_f32 v153, v153, v58, v59
	v_max3_f32 v153, v153, v60, v61
	v_max3_f32 v153, v153, v62, v63
	v_max3_f32 v153, v153, v64, v65
	v_max3_f32 v153, v153, v34, v35
	v_max3_f32 v153, v153, v36, v37
	v_max3_f32 v153, v153, v38, v39
	v_max3_f32 v153, v153, v40, v41
	v_max3_f32 v153, v153, v42, v43
	v_max3_f32 v153, v153, v44, v45
	v_max3_f32 v153, v153, v46, v47
	v_max3_f32 v153, v153, v48, v49
	ds_bpermute_b32 v162, v170, v153
	s_waitcnt lgkmcnt(0)
	v_max_f32_e32 v162, v162, v162
	v_max_f32_e32 v153, v153, v162
	v_cmp_lt_f32_e32 vcc, s98, v153
	s_cbranch_vccz .LBB0_891
	v_max_f32_e32 v162, s99, v153
	v_sub_f32_e32 v153, 0, v162
	v_min_f32_e32 v153, 0, v153
	v_exp_f32_e32 v153, v153
	v_sub_f32_e32 v206, v206, v162
	v_add_f32_e32 v151, v151, v162
	v_mov_b32_e32 v207, v206
	v_mov_b32_e32 v208, v206
	v_mov_b32_e32 v209, v206
	v_mov_b32_e32 v210, v206
	v_mov_b32_e32 v211, v206
	v_mov_b32_e32 v212, v206
	v_mov_b32_e32 v213, v206
	v_mov_b32_e32 v214, v206
	v_mov_b32_e32 v215, v206
	v_mov_b32_e32 v216, v206
	v_mov_b32_e32 v217, v206
	v_mov_b32_e32 v218, v206
	v_mov_b32_e32 v219, v206
	v_mov_b32_e32 v220, v206
	v_mov_b32_e32 v221, v206
	v_mul_f32_e32 v0, v0, v153
	v_mul_f32_e32 v32, v32, v153
	v_mul_f32_e32 v33, v33, v153
	v_mul_f32_e32 v30, v30, v153
	v_mul_f32_e32 v31, v31, v153
	v_mul_f32_e32 v28, v28, v153
	v_mul_f32_e32 v29, v29, v153
	v_mul_f32_e32 v26, v26, v153
	v_mul_f32_e32 v27, v27, v153
	v_mul_f32_e32 v24, v24, v153
	v_mul_f32_e32 v25, v25, v153
	v_mul_f32_e32 v22, v22, v153
	v_mul_f32_e32 v23, v23, v153
	v_mul_f32_e32 v20, v20, v153
	v_mul_f32_e32 v21, v21, v153
	v_mul_f32_e32 v18, v18, v153
	v_mul_f32_e32 v19, v19, v153
	v_mul_f32_e32 v16, v16, v153
	v_mul_f32_e32 v17, v17, v153
	v_mul_f32_e32 v14, v14, v153
	v_mul_f32_e32 v15, v15, v153
	v_mul_f32_e32 v12, v12, v153
	v_mul_f32_e32 v13, v13, v153
	v_mul_f32_e32 v10, v10, v153
	v_mul_f32_e32 v11, v11, v153
	v_mul_f32_e32 v8, v8, v153
	v_mul_f32_e32 v9, v9, v153
	v_mul_f32_e32 v6, v6, v153
	v_mul_f32_e32 v7, v7, v153
	v_mul_f32_e32 v4, v4, v153
	v_mul_f32_e32 v5, v5, v153
	v_mul_f32_e32 v2, v2, v153
	v_mul_f32_e32 v3, v3, v153
	v_sub_f32_e32 v50, v50, v162
	v_sub_f32_e32 v51, v51, v162
	v_sub_f32_e32 v52, v52, v162
	v_sub_f32_e32 v53, v53, v162
	v_sub_f32_e32 v54, v54, v162
	v_sub_f32_e32 v55, v55, v162
	v_sub_f32_e32 v56, v56, v162
	v_sub_f32_e32 v57, v57, v162
	v_sub_f32_e32 v58, v58, v162
	v_sub_f32_e32 v59, v59, v162
	v_sub_f32_e32 v60, v60, v162
	v_sub_f32_e32 v61, v61, v162
	v_sub_f32_e32 v62, v62, v162
	v_sub_f32_e32 v63, v63, v162
	v_sub_f32_e32 v64, v64, v162
	v_sub_f32_e32 v65, v65, v162
	v_sub_f32_e32 v34, v34, v162
	v_sub_f32_e32 v35, v35, v162
	v_sub_f32_e32 v36, v36, v162
	v_sub_f32_e32 v37, v37, v162
	v_sub_f32_e32 v38, v38, v162
	v_sub_f32_e32 v39, v39, v162
	v_sub_f32_e32 v40, v40, v162
	v_sub_f32_e32 v41, v41, v162
	v_sub_f32_e32 v42, v42, v162
	v_sub_f32_e32 v43, v43, v162
	v_sub_f32_e32 v44, v44, v162
	v_sub_f32_e32 v45, v45, v162
	v_sub_f32_e32 v46, v46, v162
	v_sub_f32_e32 v47, v47, v162
	v_sub_f32_e32 v48, v48, v162
	v_sub_f32_e32 v49, v49, v162
	s_mov_b32 s98, 0x41000000
	s_mov_b32 s99, 0
.LBB0_891:
	v_exp_f32_e32 v50, v50
	v_exp_f32_e32 v51, v51
	v_exp_f32_e32 v52, v52
	v_exp_f32_e32 v53, v53
	v_exp_f32_e32 v54, v54
	v_exp_f32_e32 v55, v55
	v_exp_f32_e32 v56, v56
	v_exp_f32_e32 v57, v57
	v_exp_f32_e32 v58, v58
	v_exp_f32_e32 v59, v59
	v_exp_f32_e32 v60, v60
	v_exp_f32_e32 v61, v61
	v_exp_f32_e32 v62, v62
	v_exp_f32_e32 v63, v63
	v_exp_f32_e32 v64, v64
	v_exp_f32_e32 v65, v65
	v_exp_f32_e32 v34, v34
	v_exp_f32_e32 v35, v35
	v_exp_f32_e32 v36, v36
	v_exp_f32_e32 v37, v37
	v_exp_f32_e32 v38, v38
	v_exp_f32_e32 v39, v39
	v_exp_f32_e32 v40, v40
	v_exp_f32_e32 v41, v41
	v_exp_f32_e32 v42, v42
	v_exp_f32_e32 v43, v43
	v_exp_f32_e32 v44, v44
	v_exp_f32_e32 v45, v45
	v_exp_f32_e32 v46, v46
	v_exp_f32_e32 v47, v47
	v_exp_f32_e32 v48, v48
	v_exp_f32_e32 v49, v49
	v_cvt_pk_bf16_f32 v162, v50, v51
	v_cvt_pk_bf16_f32 v163, v52, v53
	v_cvt_pk_bf16_f32 v164, v54, v55
	v_cvt_pk_bf16_f32 v165, v56, v57
	v_cvt_pk_bf16_f32 v174, v58, v59
	v_cvt_pk_bf16_f32 v175, v60, v61
	v_cvt_pk_bf16_f32 v176, v62, v63
	v_cvt_pk_bf16_f32 v177, v64, v65
	v_cvt_pk_bf16_f32 v178, v34, v35
	v_cvt_pk_bf16_f32 v179, v36, v37
	v_cvt_pk_bf16_f32 v180, v38, v39
	v_cvt_pk_bf16_f32 v181, v40, v41
	v_cvt_pk_bf16_f32 v182, v42, v43
	v_cvt_pk_bf16_f32 v183, v44, v45
	v_cvt_pk_bf16_f32 v184, v46, v47
	v_cvt_pk_bf16_f32 v185, v48, v49
	s_setprio 1
	v_mfma_f32_32x32x16_bf16 v[2:17], v[126:129], v[162:165], v[2:17]
	v_mfma_f32_32x32x16_bf16 v[18:33], v[122:125], v[162:165], v[18:33]
	v_mfma_f32_32x32x16_bf16 v[2:17], v[114:117], v[174:177], v[2:17]
	v_mfma_f32_32x32x16_bf16 v[18:33], v[118:121], v[174:177], v[18:33]
	v_mfma_f32_32x32x16_bf16 v[2:17], v[110:113], v[178:181], v[2:17]
	v_mfma_f32_32x32x16_bf16 v[18:33], v[106:109], v[178:181], v[18:33]
	v_mfma_f32_32x32x16_bf16 v[2:17], v[102:105], v[182:185], v[2:17]
	v_mfma_f32_32x32x16_bf16 v[18:33], v[98:101], v[182:185], v[18:33]
	s_setprio 0
	s_andn2_b64 vcc, exec, s[14:15]
	s_cbranch_vccnz .LBB0_882
	ds_write_b128 v171, v[74:77]
	ds_write2_b64 v149, v[90:91], v[92:93] offset1:1
	s_branch .LBB0_882
